# weight-conversion stores in the in-proj phase made non-temporal (less L2 pollution next to the GEMM), on v65
# speedup vs baseline: 1.0009x; 1.0009x over previous
; #define LAS __attribute__((address_space(3)))
; __device__ __forceinline__ unsigned pk2(float lo, float hi) { return pg8::cvt_pk_bf16(lo, hi); }
; __device__ __forceinline__ void transpose_tile(const float* __restrict__ W, int K, int N, bf16* __restrict__ WT, const float* __restrict__ ga, const float* __restrict__ gb, int gsplit, LAS float* scr, int item, int lane) {
;     ...
;     for (int j = 0; j < 8; ++j) { const int n = (lane >> 3) + 8 * j; const LAS float* sp = scr + (8 * kc) * 65 + n;
;         v4u o; o.x = pk2(sp[0 * 65], sp[1 * 65]); o.y = pk2(sp[2 * 65], sp[3 * 65]); o.z = pk2(sp[4 * 65], sp[5 * 65]); o.w = pk2(sp[6 * 65], sp[7 * 65]);
;         *(v4u*)(WT + (size_t)(n0 + n) * K + k0 + 8 * kc) = o; }
.Lcvb_nonext:
	ds_read2_b32 v[80:81], v118 offset0:0 offset1:65
	ds_read2_b32 v[82:83], v118 offset0:130 offset1:195
	ds_read2_b32 v[84:85], v119 offset0:4 offset1:69
	ds_read2_b32 v[86:87], v119 offset0:134 offset1:199
	ds_read2_b32 v[88:89], v118 offset0:8 offset1:73
	ds_read2_b32 v[90:91], v118 offset0:138 offset1:203
	ds_read2_b32 v[92:93], v119 offset0:12 offset1:77
	ds_read2_b32 v[94:95], v119 offset0:142 offset1:207
	ds_read2_b32 v[96:97], v118 offset0:16 offset1:81
	ds_read2_b32 v[98:99], v118 offset0:146 offset1:211
	ds_read2_b32 v[100:101], v119 offset0:20 offset1:85
	ds_read2_b32 v[102:103], v119 offset0:150 offset1:215
	s_waitcnt lgkmcnt(8)
	v_cvt_pk_bf16_f32 v104, v80, v81
	v_cvt_pk_bf16_f32 v105, v82, v83
	v_cvt_pk_bf16_f32 v106, v84, v85
	v_cvt_pk_bf16_f32 v107, v86, v87
	global_store_dwordx4 v121, v[104:107], s[66:67] nt
	v_add_u32_e32 v121, s71, v121
	ds_read2_b32 v[80:81], v118 offset0:24 offset1:89
	ds_read2_b32 v[82:83], v118 offset0:154 offset1:219
	ds_read2_b32 v[84:85], v119 offset0:28 offset1:93
	ds_read2_b32 v[86:87], v119 offset0:158 offset1:223
	s_waitcnt lgkmcnt(8)
	v_cvt_pk_bf16_f32 v108, v88, v89
	v_cvt_pk_bf16_f32 v109, v90, v91
	v_cvt_pk_bf16_f32 v110, v92, v93
	v_cvt_pk_bf16_f32 v111, v94, v95
	global_store_dwordx4 v121, v[108:111], s[66:67] nt
	v_add_u32_e32 v121, s71, v121
	ds_read2_b32 v[88:89], v118 offset0:32 offset1:97
	ds_read2_b32 v[90:91], v118 offset0:162 offset1:227
	ds_read2_b32 v[92:93], v119 offset0:36 offset1:101
	ds_read2_b32 v[94:95], v119 offset0:166 offset1:231
	s_waitcnt lgkmcnt(8)
	v_cvt_pk_bf16_f32 v104, v96, v97
	v_cvt_pk_bf16_f32 v105, v98, v99
	v_cvt_pk_bf16_f32 v106, v100, v101
	v_cvt_pk_bf16_f32 v107, v102, v103
	global_store_dwordx4 v121, v[104:107], s[66:67] nt
	v_add_u32_e32 v121, s71, v121
	ds_read2_b32 v[96:97], v118 offset0:40 offset1:105
	ds_read2_b32 v[98:99], v118 offset0:170 offset1:235
	ds_read2_b32 v[100:101], v119 offset0:44 offset1:109
	ds_read2_b32 v[102:103], v119 offset0:174 offset1:239
	s_waitcnt lgkmcnt(8)
	v_cvt_pk_bf16_f32 v108, v80, v81
	v_cvt_pk_bf16_f32 v109, v82, v83
	v_cvt_pk_bf16_f32 v110, v84, v85
	v_cvt_pk_bf16_f32 v111, v86, v87
	global_store_dwordx4 v121, v[108:111], s[66:67] nt
	v_add_u32_e32 v121, s71, v121
	ds_read2_b32 v[80:81], v118 offset0:48 offset1:113
	ds_read2_b32 v[82:83], v118 offset0:178 offset1:243
	ds_read2_b32 v[84:85], v119 offset0:52 offset1:117
	ds_read2_b32 v[86:87], v119 offset0:182 offset1:247
	s_waitcnt lgkmcnt(8)
	v_cvt_pk_bf16_f32 v104, v88, v89
	v_cvt_pk_bf16_f32 v105, v90, v91
	v_cvt_pk_bf16_f32 v106, v92, v93
	v_cvt_pk_bf16_f32 v107, v94, v95
	global_store_dwordx4 v121, v[104:107], s[66:67] nt
	v_add_u32_e32 v121, s71, v121
	ds_read2_b32 v[88:89], v118 offset0:56 offset1:121
	ds_read2_b32 v[90:91], v118 offset0:186 offset1:251
	ds_read2_b32 v[92:93], v119 offset0:60 offset1:125
	ds_read2_b32 v[94:95], v119 offset0:190 offset1:255
	s_waitcnt lgkmcnt(8)
	v_cvt_pk_bf16_f32 v108, v96, v97
	v_cvt_pk_bf16_f32 v109, v98, v99
	v_cvt_pk_bf16_f32 v110, v100, v101
	v_cvt_pk_bf16_f32 v111, v102, v103
	global_store_dwordx4 v121, v[108:111], s[66:67] nt
	v_add_u32_e32 v121, s71, v121
	s_waitcnt lgkmcnt(4)
	v_cvt_pk_bf16_f32 v104, v80, v81
	v_cvt_pk_bf16_f32 v105, v82, v83
	v_cvt_pk_bf16_f32 v106, v84, v85
	v_cvt_pk_bf16_f32 v107, v86, v87
	global_store_dwordx4 v121, v[104:107], s[66:67] nt
	v_add_u32_e32 v121, s71, v121
	s_waitcnt lgkmcnt(0)
	v_cvt_pk_bf16_f32 v108, v88, v89
	v_cvt_pk_bf16_f32 v109, v90, v91
	v_cvt_pk_bf16_f32 v110, v92, v93
	v_cvt_pk_bf16_f32 v111, v94, v95
	global_store_dwordx4 v121, v[108:111], s[66:67] nt
	s_cmp_eq_u32 s87, 0
	s_cbranch_scc1 .Lcvb_fin
	s_add_u32 s60, s60, s61
	s_branch .Lcvb_tile
